# nt hint on read-once full-line loads: x rows (prep, mid), HGRN phase A g/k/v, phase C q/k/g/v
# speedup vs baseline: 1.0254x; 1.0189x over previous
; #define LAS __attribute__((address_space(3)))
; DI int opaque_tid() { int t = threadIdx.x; asm volatile("" : "+v"(t)); return t; }
; DI void load_g4(const bf16_t* G  , int w, int dgrp, int rsub, u32x4 (&graw)[4]) {
;     const bf16_t* gp = G + (size_t)(16 * w + 4 * rsub) * D + 8 * dgrp;
; #pragma unroll
;     for (int rr = 0; rr < 4; ++rr) graw[rr] = *(const u32x4*)(gp + (size_t)rr * D);
; }
; DI void hgrn_phase_a(const Params& p, LAS unsigned char* lds) {
;     using namespace hg;
;     unsigned char* ws = p.ws;
;     const int tid = opaque_tid(), w = tid >> 6, lane = tid & 63, dgrp = lane & 15, rsub = lane >> 4, r32 = lane & 31, hi = lane >> 5;
;     LAS float* Wl = (LAS float*)(lds + OFF_W);
;     bf16_t* Ug = (bf16_t*)p.out; float* dec = (float*)(ws + OFF_DEC);
;     u32x4 gnext[4];
;     { const int it2 = blockIdx.x, n = it2 & 31, bh = it2 >> 5, h = bh & 7, b = bh >> 3;
;       load_g4((const bf16_t*)(ws + OFF_GF) + ((size_t)b * LP + 128 * n) * D + h * DH, w, dgrp, rsub, gnext); }
.LBB0_282:
	s_or_b64 exec, exec, s[0:1]
	v_readlane_b32 s0, v226, 0
	v_readlane_b32 s1, v226, 1
	s_waitcnt lgkmcnt(0)
	v_mov_b32_e32 v0, v146
	s_and_b64 vcc, exec, s[0:1]
	v_mbcnt_lo_u32_b32 v147, -1, 0
	s_barrier
	s_cbranch_vccnz .LBB0_291
	v_and_b32_e32 v5, 15, v0
	v_mov_b32_e32 v123, 0
	v_lshlrev_b32_e32 v124, 5, v5
	v_mov_b32_e32 v125, v123
	v_lshl_add_u64 v[6:7], s[30:31], 0, v[124:125]
	s_mov_b64 s[0:1], 0x3a901000
	v_lshl_add_u64 v[126:127], v[6:7], 0, s[0:1]
	s_ashr_i32 s0, s2, 8
	s_lshl_b32 s3, s2, 7
	s_mul_hi_i32 s1, s0, 0x1080
	s_mulk_i32 s0, 0x1080
	s_and_b32 s3, s3, 0xf80
	s_add_u32 s0, s0, s3
	s_addc_u32 s1, s1, 0
	v_ashrrev_i32_e32 v182, 6, v0
	s_lshl_b64 s[0:1], s[0:1], 11
	v_bfe_u32 v10, v0, 4, 2
	v_lshlrev_b32_e32 v2, 4, v182
	s_add_u32 s0, s26, s0
	v_lshl_or_b32 v2, v10, 2, v2
	s_addc_u32 s1, s27, s1
	s_and_b32 s3, s33, 0x700
	v_ashrrev_i32_e32 v3, 31, v2
	s_add_u32 s0, s0, s3
	v_lshlrev_b64 v[120:121], 11, v[2:3]
	s_addc_u32 s1, s1, 0
	v_lshl_add_u64 v[6:7], s[0:1], 0, v[120:121]
	v_lshlrev_b32_e32 v122, 4, v5
	v_lshl_add_u64 v[6:7], v[6:7], 0, v[122:123]
	s_movk_i32 s0, 0x1000
	v_add_co_u32_e32 v8, vcc, s0, v6
	s_mov_b64 s[0:1], 0x19c81000
	s_nop 0
	v_addc_co_u32_e32 v9, vcc, 0, v7, vcc
	global_load_dwordx4 v[44:47], v[8:9], off offset:2048 nt
	global_load_dwordx4 v[40:43], v[8:9], off nt
	global_load_dwordx4 v[36:39], v[6:7], off offset:2048 nt
	global_load_dwordx4 v[32:35], v[6:7], off nt
	v_lshl_add_u64 v[6:7], s[30:31], 0, v[122:123]
	v_lshl_add_u64 v[130:131], v[6:7], 0, s[0:1]
	v_mbcnt_hi_u32_b32 v6, -1, v147
	v_add_u32_e32 v7, -16, v6
	v_and_b32_e32 v9, 64, v6
	v_cmp_lt_i32_e32 vcc, v7, v9
	s_movk_i32 s3, 0xffe0
	v_and_b32_e32 v1, 63, v0
	v_cndmask_b32_e32 v7, v7, v6, vcc
	v_lshlrev_b32_e32 v125, 2, v7
	v_subrev_u32_e32 v7, 32, v6
	v_cmp_lt_i32_e32 vcc, v7, v9
	v_lshlrev_b32_e32 v4, 3, v5
	v_and_b32_e32 v12, 31, v0
	v_cndmask_b32_e32 v6, v7, v6, vcc
	v_lshlrev_b32_e32 v183, 2, v6
	v_lshlrev_b32_e32 v6, 1, v182
	v_and_b32_e32 v14, 2, v6
	v_ashrrev_i32_e32 v7, 2, v0
	v_bfe_u32 v8, v0, 5, 1
	v_lshlrev_b32_e32 v13, 1, v2
	v_cmp_gt_u32_e32 vcc, 64, v0
	v_bfi_b32 v0, s3, v7, v0
	s_movk_i32 s3, 0x110
	v_mul_u32_u24_e32 v5, 0x880, v5
	v_or_b32_e32 v22, 1, v14
	v_and_b32_e32 v6, 0xffffffe0, v7
	v_mul_lo_u32 v7, v0, s3
	v_lshlrev_b32_e32 v18, 7, v12
	v_xad_u32 v5, v13, v122, v5
	v_lshl_or_b32 v13, v14, 5, v12
	v_lshl_or_b32 v12, v22, 5, v12
	v_add_u32_e32 v17, 0, v7
	v_ashrrev_i32_e32 v7, 31, v6
	v_mul_u32_u24_e32 v19, 0x110, v13
	v_lshlrev_b32_e32 v13, 1, v13
	v_mul_u32_u24_e32 v23, 0x110, v12
	v_lshlrev_b32_e32 v12, 1, v12
	v_cmp_eq_u32_e64 s[8:9], 3, v10
	v_lshlrev_b32_e32 v15, 4, v8
	v_lshlrev_b32_e32 v16, 1, v0
	v_lshl_add_u64 v[132:133], v[6:7], 1, s[28:29]
	v_lshlrev_b32_e32 v0, 3, v8
	v_lshlrev_b64 v[6:7], 10, v[2:3]
	v_or_b32_e32 v8, 1, v2
	v_or_b32_e32 v10, 2, v2
	v_or_b32_e32 v2, 3, v2
	v_and_b32_e32 v13, 0xb0, v13
	s_movk_i32 s3, 0xf0
	v_and_b32_e32 v12, 0xf0, v12
	s_add_i32 s0, 0, 0x1a800
	v_ashrrev_i32_e32 v9, 31, v8
	v_ashrrev_i32_e32 v11, 31, v10
	v_ashrrev_i32_e32 v3, 31, v2
	v_bitop3_b32 v20, v16, v15, s3 bitop3:0x6c
	v_xad_u32 v21, v13, v15, 0
	v_xad_u32 v24, v12, v15, 0
	v_or_b32_e32 v25, 32, v15
	v_or_b32_e32 v28, 64, v15
	v_or_b32_e32 v31, 0x60, v15
	v_or_b32_e32 v50, 0x80, v15
	v_or_b32_e32 v53, 0xa0, v15
	v_or_b32_e32 v56, 0xc0, v15
	v_or_b32_e32 v15, 0xe0, v15
	v_cmp_gt_u32_e64 s[4:5], 16, v1
	v_cmp_lt_u32_e64 s[6:7], 31, v1
	v_lshl_add_u32 v1, v182, 9, s0
	v_lshlrev_b64 v[8:9], 10, v[8:9]
	v_lshlrev_b64 v[10:11], 10, v[10:11]
	v_lshlrev_b64 v[2:3], 10, v[2:3]
	v_bitop3_b32 v26, v16, v25, s3 bitop3:0x6c
	v_xad_u32 v27, v13, v25, 0
	v_xad_u32 v25, v12, v25, 0
	v_bitop3_b32 v29, v16, v28, s3 bitop3:0x6c
	v_xad_u32 v30, v13, v28, 0
	v_xad_u32 v28, v12, v28, 0
	v_bitop3_b32 v48, v16, v31, s3 bitop3:0x6c
	v_xad_u32 v49, v13, v31, 0
	v_xad_u32 v31, v12, v31, 0
	v_bitop3_b32 v51, v16, v50, s3 bitop3:0x6c
	v_xad_u32 v52, v13, v50, 0
	v_xad_u32 v50, v12, v50, 0
	v_bitop3_b32 v54, v16, v53, s3 bitop3:0x6c
	v_xad_u32 v55, v13, v53, 0
	v_xad_u32 v53, v12, v53, 0
	v_bitop3_b32 v57, v16, v56, s3 bitop3:0x6c
	v_xad_u32 v58, v13, v56, 0
	v_xad_u32 v56, v12, v56, 0
	v_bitop3_b32 v16, v16, v15, s3 bitop3:0x6c
	v_xad_u32 v13, v13, v15, 0
	v_xad_u32 v15, v12, v15, 0
	v_lshl_or_b32 v12, v14, 12, v18
	v_lshl_or_b32 v14, v22, 12, v18
	s_add_i32 s3, s2, s54
	v_lshl_add_u64 v[128:129], s[50:51], 0, v[122:123]
	s_and_b64 s[0:1], vcc, s[4:5]
	s_lshl_b32 s11, s3, 7
	s_lshl_b32 s18, s54, 7
	s_lshl_b32 s19, s3, 2
	s_lshl_b32 s20, s54, 2
	v_lshlrev_b64 v[134:135], 1, v[6:7]
	v_lshlrev_b64 v[136:137], 1, v[8:9]
	v_lshlrev_b64 v[138:139], 1, v[10:11]
	v_lshlrev_b64 v[140:141], 1, v[2:3]
	v_add_u32_e32 v184, v1, v124
	v_lshlrev_b32_e32 v142, 1, v4
	v_add_u32_e32 v185, 0, v5
	s_mov_b32 s21, 0xffff0000
	v_add_u32_e32 v186, v17, v20
	v_add_u32_e32 v187, v21, v19
	v_add_u32_e32 v188, v24, v23
	v_add_u32_e32 v189, v17, v26
	v_add_u32_e32 v190, v27, v19
	v_add_u32_e32 v191, v25, v23
	v_add_u32_e32 v192, v17, v29
	v_add_u32_e32 v193, v30, v19
	v_add_u32_e32 v194, v28, v23
	v_add_u32_e32 v195, v17, v48
	v_add_u32_e32 v196, v49, v19
	v_add_u32_e32 v197, v31, v23
	v_add_u32_e32 v198, v17, v51
	v_add_u32_e32 v199, v52, v19
	v_add_u32_e32 v200, v50, v23
	v_add_u32_e32 v201, v17, v54
	v_add_u32_e32 v202, v55, v19
	v_add_u32_e32 v203, v53, v23
	v_add_u32_e32 v204, v17, v57
	v_add_u32_e32 v205, v58, v19
	v_add_u32_e32 v206, v56, v23
	v_add_u32_e32 v207, v17, v16
	v_add_u32_e32 v208, v13, v19
	v_add_u32_e32 v209, v15, v23
	v_lshlrev_b32_e32 v122, 1, v12
	v_lshlrev_b32_e32 v144, 1, v0
	v_lshlrev_b32_e32 v148, 1, v14
	s_mov_b32 s35, s2
	s_waitcnt vmcnt(0)
	s_branch .LBB0_285

; #define LAS __attribute__((address_space(3)))
; DI float h_lo(unsigned u) { const f16x2_t h = __builtin_bit_cast(f16x2_t, u); return (float)h[0]; }
; DI float h_hi(unsigned u) { const f16x2_t h = __builtin_bit_cast(f16x2_t, u); return (float)h[1]; }
; DI void cumsum4x8(const u32x4 (&graw)[4], int w, int dgrp, int rsub, LAS float* Wl, float (&b)[4][8], float (&blast)[8]) {
; #pragma unroll
;     for (int rr = 0; rr < 4; ++rr) { const u32x4 a = graw[rr];
;         b[rr][0] = h_lo(a.x); b[rr][1] = h_hi(a.x); b[rr][2] = h_lo(a.y); b[rr][3] = h_hi(a.y); b[rr][4] = h_lo(a.z); b[rr][5] = h_hi(a.z); b[rr][6] = h_lo(a.w); b[rr][7] = h_hi(a.w); }
; #pragma unroll
;     for (int rr = 1; rr < 4; ++rr)
; #pragma unroll
;         for (int j = 0; j < 8; ++j) b[rr][j] += b[rr - 1][j];
;     float incl[8];
; #pragma unroll
;     for (int j = 0; j < 8; ++j) { float x = b[3][j]; float y = __shfl_up(x, 16); x += (rsub >= 1) ? y : 0.f; y = __shfl_up(x, 32); x += (rsub >= 2) ? y : 0.f; incl[j] = x; }
;     if (rsub == 3) { *(LAS f32x4*)(Wl + w * 128 + 8 * dgrp) = (f32x4){incl[0], incl[1], incl[2], incl[3]}; *(LAS f32x4*)(Wl + w * 128 + 8 * dgrp + 4) = (f32x4){incl[4], incl[5], incl[6], incl[7]}; }
; DI void hgrn_phase_a(const Params& p, LAS unsigned char* lds) {
;     ...
;     for (int it2 = blockIdx.x; it2 < NB * NH * (NCHUNK - 1); it2 += gridDim.x) {
;         const int n = it2 & 31, bh = it2 >> 5, h = bh & 7, b = bh >> 3, it = bh * NCHUNK + n;
;         const size_t rowbase = ((size_t)b * LP + 128 * n) * D + h * DH;
;         const bf16_t* Kg = (const bf16_t*)(ws + OFF_K) + rowbase; const bf16_t* Vg = (const bf16_t*)(ws + OFF_V) + rowbase;
;         const int row0 = 16 * w + 4 * rsub;
;         u32x4 graw[4];
; #pragma unroll
;         for (int rr = 0; rr < 4; ++rr) graw[rr] = gnext[rr];
;         u32x4 kw[4], vw[4];
; #pragma unroll
;         for (int rr = 0; rr < 4; ++rr) { kw[rr] = *(const u32x4*)(Kg + (size_t)(row0 + rr) * D + 8 * dgrp); vw[rr] = *(const u32x4*)(Vg + (size_t)(row0 + rr) * D + 8 * dgrp); }
;         __syncthreads();
;         float bb[4][8], blast[8];
;         cumsum4x8(graw, w, dgrp, rsub, Wl, bb, blast);
.LBB0_285:
	s_and_b32 s14, s35, 31
	s_ashr_i32 s3, s35, 8
	s_ashr_i32 s15, s35, 5
	s_mul_hi_i32 s13, s3, 0x1080
	s_mulk_i32 s3, 0x1080
	s_lshl_b32 s12, s14, 7
	s_add_u32 s12, s3, s12
	s_addc_u32 s13, s13, 0
	s_lshl_b32 s3, s15, 8
	s_lshl_b64 s[12:13], s[12:13], 11
	s_and_b32 s3, s3, 0x700
	s_or_b32 s12, s12, s3
	v_lshl_add_u64 v[24:25], v[128:129], 0, s[12:13]
	v_lshl_add_u64 v[26:27], v[130:131], 0, s[12:13]
	v_lshl_add_u64 v[0:1], v[24:25], 0, v[134:135]
	v_lshl_add_u64 v[2:3], v[26:27], 0, v[134:135]
	v_lshl_add_u64 v[4:5], v[24:25], 0, v[136:137]
	v_lshl_add_u64 v[6:7], v[26:27], 0, v[136:137]
	v_lshl_add_u64 v[8:9], v[24:25], 0, v[138:139]
	v_lshl_add_u64 v[10:11], v[26:27], 0, v[138:139]
	v_lshl_add_u64 v[24:25], v[24:25], 0, v[140:141]
	v_lshl_add_u64 v[26:27], v[26:27], 0, v[140:141]
	global_load_dwordx4 v[16:19], v[0:1], off nt
	s_nop 0
	global_load_dwordx4 v[0:3], v[2:3], off nt
	s_nop 0
	global_load_dwordx4 v[20:23], v[4:5], off nt
	s_nop 0
	global_load_dwordx4 v[4:7], v[6:7], off nt
	s_nop 0
	global_load_dwordx4 v[12:15], v[8:9], off nt
	s_nop 0
	global_load_dwordx4 v[8:11], v[10:11], off nt
	s_nop 0
	global_load_dwordx4 v[28:31], v[24:25], off nt
	s_nop 0
	global_load_dwordx4 v[24:27], v[26:27], off nt
	s_waitcnt vmcnt(12)
	v_cvt_f32_f16_sdwa v153, v32 dst_sel:DWORD dst_unused:UNUSED_PAD src0_sel:WORD_1
	v_cvt_f32_f16_e32 v152, v32
	v_cvt_f32_f16_sdwa v49, v36 dst_sel:DWORD dst_unused:UNUSED_PAD src0_sel:WORD_1
	v_cvt_f32_f16_e32 v48, v36
	v_cvt_f32_f16_sdwa v51, v40 dst_sel:DWORD dst_unused:UNUSED_PAD src0_sel:WORD_1
	v_cvt_f32_f16_e32 v50, v40
	v_cvt_f32_f16_sdwa v53, v44 dst_sel:DWORD dst_unused:UNUSED_PAD src0_sel:WORD_1
	v_cvt_f32_f16_e32 v52, v44
	v_pk_add_f32 v[156:157], v[152:153], v[48:49]
	v_cvt_f32_f16_sdwa v161, v33 dst_sel:DWORD dst_unused:UNUSED_PAD src0_sel:WORD_1
	v_pk_add_f32 v[154:155], v[156:157], v[50:51]
	v_cvt_f32_f16_e32 v160, v33
	v_pk_add_f32 v[150:151], v[154:155], v[52:53]
	ds_bpermute_b32 v48, v125, v151
	ds_bpermute_b32 v50, v125, v150
	v_cvt_f32_f16_sdwa v51, v37 dst_sel:DWORD dst_unused:UNUSED_PAD src0_sel:WORD_1
	v_cvt_f32_f16_sdwa v53, v41 dst_sel:DWORD dst_unused:UNUSED_PAD src0_sel:WORD_1
	v_cvt_f32_f16_e32 v52, v41
	s_waitcnt lgkmcnt(1)
	v_cndmask_b32_e64 v49, v48, 0, s[4:5]
	s_waitcnt lgkmcnt(0)
	v_cndmask_b32_e64 v48, v50, 0, s[4:5]
	v_cvt_f32_f16_e32 v50, v37
	v_cvt_f32_f16_sdwa v55, v45 dst_sel:DWORD dst_unused:UNUSED_PAD src0_sel:WORD_1
	v_cvt_f32_f16_e32 v54, v45
	v_pk_add_f32 v[48:49], v[150:151], v[48:49]
	v_pk_add_f32 v[164:165], v[160:161], v[50:51]
	ds_bpermute_b32 v56, v183, v48
	ds_bpermute_b32 v57, v183, v49
	v_pk_add_f32 v[162:163], v[164:165], v[52:53]
	v_cvt_f32_f16_sdwa v169, v34 dst_sel:DWORD dst_unused:UNUSED_PAD src0_sel:WORD_1
	v_pk_add_f32 v[158:159], v[162:163], v[54:55]
	ds_bpermute_b32 v52, v125, v159
	ds_bpermute_b32 v53, v125, v158
	s_waitcnt lgkmcnt(2)
	v_cndmask_b32_e64 v51, 0, v57, s[6:7]
	v_cndmask_b32_e64 v50, 0, v56, s[6:7]
	v_pk_add_f32 v[84:85], v[48:49], v[50:51]
	v_cvt_f32_f16_e32 v168, v34
	v_cvt_f32_f16_sdwa v51, v38 dst_sel:DWORD dst_unused:UNUSED_PAD src0_sel:WORD_1
	v_cvt_f32_f16_e32 v50, v38
	s_waitcnt lgkmcnt(1)
	v_cndmask_b32_e64 v49, v52, 0, s[4:5]
	s_waitcnt lgkmcnt(0)
	v_cndmask_b32_e64 v48, v53, 0, s[4:5]
	v_cvt_f32_f16_sdwa v53, v42 dst_sel:DWORD dst_unused:UNUSED_PAD src0_sel:WORD_1
	v_cvt_f32_f16_e32 v52, v42
	v_cvt_f32_f16_sdwa v55, v46 dst_sel:DWORD dst_unused:UNUSED_PAD src0_sel:WORD_1
	v_cvt_f32_f16_e32 v54, v46
	v_pk_add_f32 v[48:49], v[158:159], v[48:49]
	v_pk_add_f32 v[172:173], v[168:169], v[50:51]
	ds_bpermute_b32 v56, v183, v48
	ds_bpermute_b32 v57, v183, v49
	v_pk_add_f32 v[170:171], v[172:173], v[52:53]
	v_cvt_f32_f16_sdwa v177, v35 dst_sel:DWORD dst_unused:UNUSED_PAD src0_sel:WORD_1
	v_pk_add_f32 v[166:167], v[170:171], v[54:55]
	ds_bpermute_b32 v52, v125, v167
	s_waitcnt lgkmcnt(1)
	v_cndmask_b32_e64 v51, 0, v57, s[6:7]
	v_cndmask_b32_e64 v50, 0, v56, s[6:7]
	v_pk_add_f32 v[86:87], v[48:49], v[50:51]
	v_cvt_f32_f16_e32 v176, v35
	v_cvt_f32_f16_sdwa v51, v39 dst_sel:DWORD dst_unused:UNUSED_PAD src0_sel:WORD_1
	v_cvt_f32_f16_e32 v50, v39
	s_waitcnt lgkmcnt(0)
	v_cndmask_b32_e64 v49, v52, 0, s[4:5]
	v_cvt_f32_f16_sdwa v53, v43 dst_sel:DWORD dst_unused:UNUSED_PAD src0_sel:WORD_1
	v_cvt_f32_f16_e32 v52, v43
	v_cvt_f32_f16_sdwa v55, v47 dst_sel:DWORD dst_unused:UNUSED_PAD src0_sel:WORD_1
	v_cvt_f32_f16_e32 v54, v47
	v_pk_add_f32 v[180:181], v[176:177], v[50:51]
	ds_bpermute_b32 v48, v125, v166
	v_pk_add_f32 v[178:179], v[180:181], v[52:53]
	s_waitcnt lgkmcnt(0)
	v_pk_add_f32 v[174:175], v[178:179], v[54:55]
	ds_bpermute_b32 v50, v125, v175
	ds_bpermute_b32 v52, v125, v174
	v_cndmask_b32_e64 v48, v48, 0, s[4:5]
	v_pk_add_f32 v[48:49], v[166:167], v[48:49]
	ds_bpermute_b32 v54, v183, v48
	s_waitcnt lgkmcnt(2)
	v_cndmask_b32_e64 v51, v50, 0, s[4:5]
	s_waitcnt lgkmcnt(1)
	v_cndmask_b32_e64 v50, v52, 0, s[4:5]
	ds_bpermute_b32 v53, v183, v49
	v_pk_add_f32 v[50:51], v[174:175], v[50:51]
	ds_bpermute_b32 v55, v183, v51
	ds_bpermute_b32 v56, v183, v50
	s_waitcnt lgkmcnt(3)
	v_cndmask_b32_e64 v52, 0, v54, s[6:7]
	s_waitcnt lgkmcnt(2)
	v_cndmask_b32_e64 v53, 0, v53, s[6:7]
	v_pk_add_f32 v[108:109], v[48:49], v[52:53]
	s_waitcnt lgkmcnt(1)
	v_cndmask_b32_e64 v49, 0, v55, s[6:7]
	s_waitcnt lgkmcnt(0)
	v_cndmask_b32_e64 v48, 0, v56, s[6:7]
	v_pk_add_f32 v[110:111], v[50:51], v[48:49]
	s_barrier
	s_and_saveexec_b64 s[12:13], s[8:9]
	s_cbranch_execz .LBB0_287
	ds_write_b128 v184, v[84:87]
	ds_write_b128 v184, v[108:111] offset:16
; #define LAS __attribute__((address_space(3)))
; DI void cumsum4x8(const u32x4 (&graw)[4], int w, int dgrp, int rsub, LAS float* Wl, float (&b)[4][8], float (&blast)[8]) {
;     ...
;     __syncthreads();
;     float off[8];
; #pragma unroll
;     for (int j = 0; j < 8; ++j) { off[j] = incl[j] - b[3][j]; blast[j] = 0.f; }
;     const int ws_ = __builtin_amdgcn_readfirstlane(w);
; #pragma unroll
;     for (int w2 = 0; w2 < 8; ++w2) { const f32x4 a = *(LAS const f32x4*)(Wl + w2 * 128 + 8 * dgrp), c = *(LAS const f32x4*)(Wl + w2 * 128 + 8 * dgrp + 4);
; #pragma unroll
;         for (int j = 0; j < 8; ++j) { const float v = j < 4 ? a[j & 3] : c[j & 3]; blast[j] += v; }
;         if (w2 < ws_) {
; #pragma unroll
;             for (int j = 0; j < 8; ++j) off[j] += j < 4 ? a[j & 3] : c[j & 3]; } }
; DI void hgrn_phase_a(const Params& p, LAS unsigned char* lds) {
;     ...
;         { const int nx = it2 + (int)gridDim.x;
;           if (nx < NB * NH * (NCHUNK - 1)) { const int n2 = nx & 31, bh2 = nx >> 5, h2 = bh2 & 7, b2 = bh2 >> 3;
;               load_g4((const bf16_t*)(ws + OFF_GF) + ((size_t)b2 * LP + 128 * n2) * D + h2 * DH, w, dgrp, rsub, gnext); } }
.LBB0_287:
	s_or_b64 exec, exec, s[12:13]
	v_add_u32_e32 v48, 0, v124
	v_add_u32_e32 v48, 0x1a800, v48
	s_waitcnt lgkmcnt(0)
	s_barrier
	ds_read_b128 v[116:119], v48
	ds_read_b128 v[112:115], v48 offset:16
	ds_read_b128 v[104:107], v48 offset:512
	ds_read_b128 v[100:103], v48 offset:528
	ds_read_b128 v[96:99], v48 offset:1024
	ds_read_b128 v[92:95], v48 offset:1040
	ds_read_b128 v[88:91], v48 offset:1536
	ds_read_b128 v[80:83], v48 offset:1552
	ds_read_b128 v[76:79], v48 offset:2048
	ds_read_b128 v[72:75], v48 offset:2064
	ds_read_b128 v[68:71], v48 offset:2560
	ds_read_b128 v[64:67], v48 offset:2576
	ds_read_b128 v[60:63], v48 offset:3072
	ds_read_b128 v[56:59], v48 offset:3088
	ds_read_b128 v[52:55], v48 offset:3584
	ds_read_b128 v[48:51], v48 offset:3600
	s_add_i32 s35, s35, s54
	s_cmpk_gt_i32 s35, 0xfff
	s_cselect_b64 s[12:13], -1, 0
	v_readfirstlane_b32 s3, v182
	s_and_b64 vcc, exec, s[12:13]
	s_ashr_i32 s16, s35, 8
	s_mul_hi_i32 s17, s16, 0x1080
	s_mulk_i32 s16, 0x1080
	s_and_b32 s58, s11, 0xf80
	s_add_u32 s16, s16, s58
	s_addc_u32 s17, s17, 0
	s_lshl_b64 s[16:17], s[16:17], 11
	s_add_u32 s16, s26, s16
	s_addc_u32 s17, s27, s17
	s_and_b32 s58, s19, 0x380
	s_lshl_b32 s58, s58, 1
	s_add_u32 s16, s16, s58
	s_addc_u32 s17, s17, 0
	v_lshl_add_u64 v[32:33], s[16:17], 0, v[120:121]
	v_mov_b32_e32 v143, v123
	v_lshl_add_u64 v[40:41], v[32:33], 0, v[142:143]
	v_add_co_u32_e32 v44, vcc, 0x1000, v40
	global_load_dwordx4 v[32:35], v[40:41], off nt
	global_load_dwordx4 v[36:39], v[40:41], off offset:2048 nt
	v_addc_co_u32_e32 v45, vcc, 0, v41, vcc
	global_load_dwordx4 v[40:43], v[44:45], off nt
	s_nop 0
	global_load_dwordx4 v[44:47], v[44:45], off offset:2048 nt

; #define LAS __attribute__((address_space(3)))
; DI int opaque_tid() { int t = threadIdx.x; asm volatile("" : "+v"(t)); return t; }
; DI void hgrn_phase_c(const Params& p, LAS unsigned char* lds) {
;     using namespace hg;
;     unsigned char* ws = p.ws;
;     const int tid = opaque_tid(), w = tid >> 6, lane = tid & 63, dgrp = lane & 15, rsub = lane >> 4, l15 = lane & 15, g4 = lane >> 4;
;     const int wsc = __builtin_amdgcn_readfirstlane(w);
;     LAS float* Wl = (LAS float*)(lds + OFF_W); LAS float* cv = (LAS float*)(lds + OFF_CV); LAS float* part = (LAS float*)(lds + OFF_PART);
;     const bf16_t* Sg = (const bf16_t*)p.out;
;     const bf16_t* Gt = (const bf16_t*)(ws + OFF_GATE); bf16_t* Og = (bf16_t*)(ws + OFF_ABUF);
;     const f32x4 on = *(const f32x4*)(p.honorm + 16 * w + 4 * g4);
;     u32x4 gnext[4];
;     { const int it = blockIdx.x, n = it % NCHUNK, bh = it / NCHUNK, h = bh & 7, b = bh >> 3;
;       load_g4((const bf16_t*)(ws + OFF_GF) + ((size_t)b * LP + 128 * n) * D + h * DH, w, dgrp, rsub, gnext); }
.LBB0_400:
	s_or_b64 exec, exec, s[0:1]
	v_mov_b32_e32 v20, v146
	s_waitcnt lgkmcnt(0)
	s_barrier
	s_cmpk_gt_i32 s2, 0x107f
	v_ashrrev_i32_e32 v136, 6, v20
	s_nop 0
	v_readfirstlane_b32 s35, v136
	s_cbranch_scc1 .LBB0_486
	s_mul_hi_i32 s0, s2, 0x3e0f83e1
	s_lshr_b32 s1, s0, 31
	s_ashr_i32 s0, s0, 3
	s_add_i32 s3, s0, s1
	s_mul_i32 s4, s3, 33
	s_sub_i32 s4, s2, s4
	s_ashr_i32 s0, s3, 3
	s_lshl_b32 s4, s4, 7
	s_mul_hi_i32 s1, s0, 0x1080
	s_mulk_i32 s0, 0x1080
	s_ashr_i32 s5, s4, 31
	s_add_u32 s0, s0, s4
	s_addc_u32 s1, s1, s5
	s_lshl_b64 s[0:1], s[0:1], 11
	v_bfe_u32 v25, v20, 4, 2
	s_add_u32 s0, s26, s0
	v_lshlrev_b32_e32 v80, 4, v136
	v_lshlrev_b32_e32 v40, 2, v25
	s_addc_u32 s1, s27, s1
	s_lshl_b32 s3, s3, 8
	v_or_b32_e32 v22, v40, v80
	s_and_b32 s3, s3, 0x700
	v_ashrrev_i32_e32 v23, 31, v22
	s_add_u32 s0, s0, s3
	v_and_b32_e32 v137, 15, v20
	v_lshlrev_b64 v[82:83], 11, v[22:23]
	s_addc_u32 s1, s1, 0
	v_mov_b32_e32 v85, 0
	v_lshl_add_u64 v[2:3], s[0:1], 0, v[82:83]
	v_lshlrev_b32_e32 v84, 4, v137
	v_lshl_add_u64 v[2:3], v[2:3], 0, v[84:85]
	s_movk_i32 s0, 0x1000
	v_add_co_u32_e32 v26, vcc, s0, v2
	v_mov_b32_e32 v0, s48
	v_mov_b32_e32 v1, s49
	v_addc_co_u32_e32 v27, vcc, 0, v3, vcc
	v_ashrrev_i32_e32 v81, 31, v80
	global_load_dwordx4 v[16:19], v[26:27], off offset:2048 nt
	global_load_dwordx4 v[12:15], v[26:27], off nt
	global_load_dwordx4 v[8:11], v[2:3], off offset:2048 nt
	global_load_dwordx4 v[4:7], v[2:3], off nt
	v_lshl_add_u64 v[0:1], v[80:81], 2, v[0:1]
	v_lshlrev_b32_e32 v26, 4, v25
	v_mov_b32_e32 v27, v85
	v_lshl_add_u64 v[0:1], v[0:1], 0, v[26:27]
	global_load_dwordx4 v[0:3], v[0:1], off nt
	v_mbcnt_hi_u32_b32 v21, -1, v147
	v_add_u32_e32 v28, -16, v21
	v_and_b32_e32 v30, 64, v21
	v_cmp_lt_i32_e32 vcc, v28, v30
	v_or_b32_e32 v29, v137, v30
	v_mov_b32_e32 v31, 0x80
	v_cndmask_b32_e32 v28, v28, v21, vcc
	v_lshlrev_b32_e32 v138, 2, v28
	v_subrev_u32_e32 v28, 32, v21
	v_cmp_lt_i32_e32 vcc, v28, v30
	s_add_i32 s68, 0, 0x1a800
	v_lshl_or_b32 v141, v29, 2, v31
	v_cndmask_b32_e32 v28, v28, v21, vcc
	v_lshlrev_b32_e32 v139, 2, v28
	v_lshlrev_b32_e32 v28, 9, v136
	s_add_i32 s3, 0, 0x19800
	v_or_b32_e32 v31, v80, v137
	v_add_u32_e32 v42, s68, v28
	v_add_u32_e32 v43, s3, v28
	v_lshlrev_b32_e32 v28, 7, v31
	v_ashrrev_i32_e32 v29, 31, v28
	v_lshl_add_u64 v[28:29], v[28:29], 1, s[28:29]
	v_lshl_add_u64 v[90:91], v[28:29], 0, v[26:27]
	v_lshl_add_u64 v[28:29], s[30:31], 0, v[84:85]
	s_mov_b64 s[0:1], 0x19c81000
	s_add_i32 s63, 0, 0x1b800
	v_lshl_add_u64 v[92:93], v[28:29], 0, s[0:1]
	s_ashr_i32 s69, s35, 1
	v_lshlrev_b32_e32 v20, 2, v20
	s_add_i32 s0, 0, 0x1c800
	v_and_b32_e32 v20, 0x1fc, v20
	s_cmp_lt_i32 s35, 4
	v_add_u32_e32 v142, s3, v20
	v_add_u32_e32 v143, s0, v20
	s_cselect_b64 s[48:49], -1, 0
	v_lshl_or_b32 v20, s35, 5, v137
	s_movk_i32 s70, 0x110
	s_add_i32 s1, 0, 0x11000
	s_lshl_b32 s3, s35, 6
	v_mul_lo_u32 v20, v20, s70
	s_add_i32 s3, s3, s1
	v_add_u32_e32 v27, s3, v20
	v_lshlrev_b32_e32 v20, 1, v22
	v_xad_u32 v46, v20, v84, 0
	v_mul_lo_u32 v20, v31, s70
	v_add_u32_e32 v48, 0, v20
	v_xor_b32_e32 v20, 16, v21
	v_add_u32_e32 v28, 64, v30
	v_cmp_lt_i32_e32 vcc, v20, v28
	v_or_b32_e32 v32, 2, v22
	v_ashrrev_i32_e32 v33, 31, v32
	v_cndmask_b32_e32 v20, v21, v20, vcc
	v_lshlrev_b32_e32 v149, 2, v20
	v_xor_b32_e32 v20, 32, v21
	v_cmp_lt_i32_e32 vcc, v20, v28
	v_or_b32_e32 v28, 1, v22
	v_ashrrev_i32_e32 v29, 31, v28
	v_cndmask_b32_e32 v20, v21, v20, vcc
	v_lshlrev_b64 v[34:35], 10, v[32:33]
	v_or_b32_e32 v36, 3, v22
	v_lshlrev_b64 v[96:97], 11, v[32:33]
	v_or_b32_e32 v32, 2, v40
	v_lshlrev_b32_e32 v45, 3, v25
	s_mov_b32 s0, 0x11000
	v_lshlrev_b32_e32 v47, 1, v31
	v_add_u32_e32 v49, s1, v26
	v_lshlrev_b32_e32 v150, 2, v20
	v_lshlrev_b64 v[20:21], 10, v[22:23]
	v_lshlrev_b64 v[30:31], 10, v[28:29]
	v_ashrrev_i32_e32 v37, 31, v36
	v_lshlrev_b64 v[94:95], 11, v[28:29]
	v_or_b32_e32 v23, 64, v26
	v_or_b32_e32 v28, 0x80, v26
	v_or_b32_e32 v29, 0xc0, v26
	v_cmp_gt_u32_e64 s[16:17], v32, v137
	v_or_b32_e32 v32, 3, v40
	s_movk_i32 s1, 0xf0
	v_mul_u32_u24_e32 v151, 0x110, v137
	v_writelane_b32 v226, s24, 2
	v_lshlrev_b32_e32 v24, 3, v137
	v_lshl_add_u32 v41, v136, 2, s63
	v_lshlrev_b32_e32 v140, 5, v137
	v_add_u32_e32 v44, 0, v84
	v_mov_b32_e32 v80, v22
	v_lshlrev_b64 v[38:39], 10, v[36:37]
	v_mul_lo_u32 v22, v22, s70
	s_add_i32 s72, s69, 4
	s_add_i32 s74, s69, 8
	s_add_i32 s76, s69, 12
	s_add_i32 s78, s69, 16
	s_add_i32 s80, s69, 20
	s_add_i32 s82, s69, 24
	v_cmp_gt_u32_e64 s[18:19], v32, v137
	v_mul_u32_u24_e32 v32, 0x880, v137
	v_bitop3_b32 v33, v47, v26, s1 bitop3:0x6c
	v_bitop3_b32 v23, v47, v23, s1 bitop3:0x6c
	v_bitop3_b32 v28, v47, v28, s1 bitop3:0x6c
	v_bitop3_b32 v29, v47, v29, s1 bitop3:0x6c
	v_add3_u32 v152, v151, v45, s0
	s_mov_b32 s0, 0x8800
	v_writelane_b32 v226, s25, 3
	s_mov_b32 s24, s33
	s_mov_b32 s33, s94
	s_mov_b32 s61, 0
	v_lshl_add_u64 v[86:87], s[46:47], 0, v[84:85]
	v_lshl_add_u64 v[88:89], s[50:51], 0, v[84:85]
	v_cmp_eq_u32_e64 s[4:5], 0, v25
	v_cmp_lt_u32_e64 s[6:7], 1, v25
	v_cmp_eq_u32_e64 s[8:9], 3, v25
	v_cmp_eq_u32_e64 s[10:11], 2, v25
	v_or_b32_e32 v144, 0xff90, v137
	v_or_b32_e32 v145, 0xffffff80, v137
	v_add_u32_e32 v148, 0, v26
	v_lshlrev_b64 v[98:99], 11, v[36:37]
	s_lshl_b32 s71, s69, 9
	s_lshl_b32 s73, s72, 9
	s_lshl_b32 s75, s74, 9
	s_lshl_b32 s77, s76, 9
	s_lshl_b32 s79, s78, 9
	s_lshl_b32 s81, s80, 9
	s_lshl_b32 s83, s82, 9
	v_cmp_gt_u32_e64 s[12:13], v40, v137
	v_cmp_lt_u32_e64 s[14:15], v40, v137
	v_lshlrev_b32_e32 v153, 5, v25
	v_add3_u32 v154, v151, v26, s0
	v_lshlrev_b64 v[100:101], 1, v[20:21]
	v_lshlrev_b64 v[102:103], 1, v[30:31]
	v_lshlrev_b64 v[104:105], 1, v[34:35]
	v_lshlrev_b64 v[106:107], 1, v[38:39]
	v_add_u32_e32 v155, v42, v140
	v_lshlrev_b32_e32 v84, 1, v24
	v_add_u32_e32 v156, v43, v140
	s_mov_b32 s85, 0xc2e60000
	s_mov_b32 s86, 0xffff0000
	v_add_u32_e32 v157, v27, v45
	v_add_u32_e32 v158, v46, v32
	v_add_u32_e32 v159, v48, v33
	v_add_u32_e32 v160, v48, v23
	v_add_u32_e32 v161, v48, v28
	v_add_u32_e32 v162, v48, v29
	v_add_u32_e32 v163, v49, v151
	v_mov_b32_e32 v164, 0x358637bd
	s_brev_b32 s62, 60
	s_mov_b32 s87, 0x800000
	s_mov_b32 s88, 0x10000
	s_mov_b32 s89, 0x18000
	s_mov_b32 s90, 0x20000
	s_mov_b32 s91, 0x28000
	v_mov_b32_e32 v165, 0x42e60000
	v_add_u32_e32 v166, v44, v22
	v_mov_b32_e32 v176, v85
	v_mov_b32_e32 v177, v85
	v_add_u32_e32 v167, v41, v140
	s_mov_b32 s20, s2
	s_branch .LBB0_403

; #define LAS __attribute__((address_space(3)))
; DI float h_lo(unsigned u) { const f16x2_t h = __builtin_bit_cast(f16x2_t, u); return (float)h[0]; }
; DI float h_hi(unsigned u) { const f16x2_t h = __builtin_bit_cast(f16x2_t, u); return (float)h[1]; }
; DI void cumsum4x8(const u32x4 (&graw)[4], int w, int dgrp, int rsub, LAS float* Wl, float (&b)[4][8], float (&blast)[8]) {
; #pragma unroll
;     for (int rr = 0; rr < 4; ++rr) { const u32x4 a = graw[rr];
;         b[rr][0] = h_lo(a.x); b[rr][1] = h_hi(a.x); b[rr][2] = h_lo(a.y); b[rr][3] = h_hi(a.y); b[rr][4] = h_lo(a.z); b[rr][5] = h_hi(a.z); b[rr][6] = h_lo(a.w); b[rr][7] = h_hi(a.w); }
; #pragma unroll
;     for (int rr = 1; rr < 4; ++rr)
; #pragma unroll
;         for (int j = 0; j < 8; ++j) b[rr][j] += b[rr - 1][j];
;     float incl[8];
; #pragma unroll
;     for (int j = 0; j < 8; ++j) { float x = b[3][j]; float y = __shfl_up(x, 16); x += (rsub >= 1) ? y : 0.f; y = __shfl_up(x, 32); x += (rsub >= 2) ? y : 0.f; incl[j] = x; }
;     if (rsub == 3) { *(LAS f32x4*)(Wl + w * 128 + 8 * dgrp) = (f32x4){incl[0], incl[1], incl[2], incl[3]}; *(LAS f32x4*)(Wl + w * 128 + 8 * dgrp + 4) = (f32x4){incl[4], incl[5], incl[6], incl[7]}; }
; DI void hgrn_phase_c(const Params& p, LAS unsigned char* lds) {
;     ...
;     for (int it = blockIdx.x; it < NITEMS; it += gridDim.x) {
;         const int n = it % NCHUNK, bh = it / NCHUNK, h = bh & 7, b = bh >> 3;
;         const size_t rowbase = ((size_t)b * LP + 128 * n) * D + h * DH;
;         const bf16_t* Qg = (const bf16_t*)(ws + OFF_Q) + rowbase; const bf16_t* Kg = (const bf16_t*)(ws + OFF_K) + rowbase; const bf16_t* Vg = (const bf16_t*)(ws + OFF_V) + rowbase;
;         const bf16_t* St = Sg + (size_t)it * 16384;
;         u32x4 graw[4];
; #pragma unroll
;         for (int rr = 0; rr < 4; ++rr) graw[rr] = gnext[rr];
;         const int row0 = 16 * w + 4 * rsub;
;         u32x4 qw[4], kw[4];
; #pragma unroll
;         for (int rr = 0; rr < 4; ++rr) { qw[rr] = *(const u32x4*)(Qg + (size_t)(row0 + rr) * D + 8 * dgrp); kw[rr] = *(const u32x4*)(Kg + (size_t)(row0 + rr) * D + 8 * dgrp); }
;         __syncthreads();
;         float bb[4][8], blast[8];
;         cumsum4x8(graw, w, dgrp, rsub, Wl, bb, blast);
.LBB0_403:
	s_mul_hi_i32 s0, s20, 0x3e0f83e1
	s_lshr_b32 s1, s0, 31
	s_ashr_i32 s0, s0, 3
	s_add_i32 s3, s0, s1
	s_mul_i32 s0, s3, 33
	s_sub_i32 s95, s20, s0
	s_ashr_i32 s93, s3, 3
	s_lshl_b32 s94, s95, 7
	s_mul_i32 s0, s93, 0x1080
	s_ashr_i32 s21, s94, 31
	s_mul_hi_i32 s1, s93, 0x1080
	s_add_u32 s0, s0, s94
	s_addc_u32 s1, s1, s21
	s_lshl_b32 s3, s3, 7
	s_and_b32 s60, s3, 0x380
	s_lshl_b64 s[0:1], s[0:1], 10
	s_or_b32 s0, s0, s60
	s_lshl_b64 s[58:59], s[0:1], 1
	v_lshl_add_u64 v[20:21], v[86:87], 0, s[58:59]
	v_lshl_add_u64 v[22:23], v[88:89], 0, s[58:59]
	v_lshl_add_u64 v[24:25], v[20:21], 0, v[100:101]
	v_lshl_add_u64 v[26:27], v[22:23], 0, v[100:101]
	global_load_dwordx4 v[48:51], v[24:25], off nt
	global_load_dwordx4 v[44:47], v[26:27], off nt
	v_lshl_add_u64 v[24:25], v[20:21], 0, v[102:103]
	v_lshl_add_u64 v[26:27], v[22:23], 0, v[102:103]
	global_load_dwordx4 v[40:43], v[24:25], off nt
	global_load_dwordx4 v[36:39], v[26:27], off nt
	v_lshl_add_u64 v[24:25], v[20:21], 0, v[104:105]
	v_lshl_add_u64 v[26:27], v[22:23], 0, v[104:105]
	v_lshl_add_u64 v[20:21], v[20:21], 0, v[106:107]
	v_lshl_add_u64 v[22:23], v[22:23], 0, v[106:107]
	global_load_dwordx4 v[32:35], v[24:25], off nt
	global_load_dwordx4 v[28:31], v[26:27], off nt
	s_nop 0
	global_load_dwordx4 v[24:27], v[20:21], off nt
	s_nop 0
	global_load_dwordx4 v[20:23], v[22:23], off nt
	s_waitcnt vmcnt(9)
	v_cvt_f32_f16_sdwa v65, v4 dst_sel:DWORD dst_unused:UNUSED_PAD src0_sel:WORD_1
	v_cvt_f32_f16_e32 v64, v4
	v_cvt_f32_f16_sdwa v53, v8 dst_sel:DWORD dst_unused:UNUSED_PAD src0_sel:WORD_1
	v_cvt_f32_f16_e32 v52, v8
	v_cvt_f32_f16_sdwa v55, v12 dst_sel:DWORD dst_unused:UNUSED_PAD src0_sel:WORD_1
	v_cvt_f32_f16_e32 v54, v12
	v_cvt_f32_f16_sdwa v57, v16 dst_sel:DWORD dst_unused:UNUSED_PAD src0_sel:WORD_1
	v_cvt_f32_f16_e32 v56, v16
	v_pk_add_f32 v[68:69], v[64:65], v[52:53]
	v_cvt_f32_f16_sdwa v67, v5 dst_sel:DWORD dst_unused:UNUSED_PAD src0_sel:WORD_1
	v_pk_add_f32 v[62:63], v[68:69], v[54:55]
	v_cvt_f32_f16_e32 v66, v5
	v_pk_add_f32 v[60:61], v[62:63], v[56:57]
	ds_bpermute_b32 v52, v138, v61
	ds_bpermute_b32 v54, v138, v60
	v_cvt_f32_f16_sdwa v55, v9 dst_sel:DWORD dst_unused:UNUSED_PAD src0_sel:WORD_1
	v_cvt_f32_f16_sdwa v57, v13 dst_sel:DWORD dst_unused:UNUSED_PAD src0_sel:WORD_1
	v_cvt_f32_f16_e32 v56, v13
	s_waitcnt lgkmcnt(1)
	v_cndmask_b32_e64 v53, v52, 0, s[4:5]
	s_waitcnt lgkmcnt(0)
	v_cndmask_b32_e64 v52, v54, 0, s[4:5]
	v_cvt_f32_f16_e32 v54, v9
	v_cvt_f32_f16_sdwa v59, v17 dst_sel:DWORD dst_unused:UNUSED_PAD src0_sel:WORD_1
	v_cvt_f32_f16_e32 v58, v17
	v_pk_add_f32 v[52:53], v[60:61], v[52:53]
	v_pk_add_f32 v[78:79], v[66:67], v[54:55]
	ds_bpermute_b32 v108, v139, v52
	v_pk_add_f32 v[76:77], v[78:79], v[56:57]
	ds_bpermute_b32 v109, v139, v53
	v_pk_add_f32 v[74:75], v[76:77], v[58:59]
	ds_bpermute_b32 v56, v138, v75
	ds_bpermute_b32 v57, v138, v74
	s_waitcnt lgkmcnt(3)
	v_cndmask_b32_e64 v54, 0, v108, s[6:7]
	s_waitcnt lgkmcnt(2)
	v_cndmask_b32_e64 v55, 0, v109, s[6:7]
	v_cvt_f32_f16_sdwa v71, v6 dst_sel:DWORD dst_unused:UNUSED_PAD src0_sel:WORD_1
	v_cvt_f32_f16_e32 v70, v6
	v_pk_add_f32 v[52:53], v[52:53], v[54:55]
	s_waitcnt lgkmcnt(1)
	v_cndmask_b32_e64 v55, v56, 0, s[4:5]
	s_waitcnt lgkmcnt(0)
	v_cndmask_b32_e64 v54, v57, 0, s[4:5]
	v_cvt_f32_f16_sdwa v57, v10 dst_sel:DWORD dst_unused:UNUSED_PAD src0_sel:WORD_1
	v_cvt_f32_f16_e32 v56, v10
	v_cvt_f32_f16_sdwa v59, v14 dst_sel:DWORD dst_unused:UNUSED_PAD src0_sel:WORD_1
	v_cvt_f32_f16_e32 v58, v14
	v_cvt_f32_f16_sdwa v109, v18 dst_sel:DWORD dst_unused:UNUSED_PAD src0_sel:WORD_1
	v_cvt_f32_f16_e32 v108, v18
	v_pk_add_f32 v[112:113], v[70:71], v[56:57]
	v_pk_add_f32 v[54:55], v[74:75], v[54:55]
	v_pk_add_f32 v[110:111], v[112:113], v[58:59]
	ds_bpermute_b32 v114, v139, v54
	ds_bpermute_b32 v115, v139, v55
	v_pk_add_f32 v[108:109], v[110:111], v[108:109]
	ds_bpermute_b32 v58, v138, v109
	v_cvt_f32_f16_sdwa v73, v7 dst_sel:DWORD dst_unused:UNUSED_PAD src0_sel:WORD_1
	s_waitcnt lgkmcnt(2)
	v_cndmask_b32_e64 v56, 0, v114, s[6:7]
	s_waitcnt lgkmcnt(1)
	v_cndmask_b32_e64 v57, 0, v115, s[6:7]
	v_cvt_f32_f16_e32 v72, v7
	v_pk_add_f32 v[54:55], v[54:55], v[56:57]
	s_waitcnt lgkmcnt(0)
	v_cndmask_b32_e64 v57, v58, 0, s[4:5]
	v_cvt_f32_f16_sdwa v59, v11 dst_sel:DWORD dst_unused:UNUSED_PAD src0_sel:WORD_1
	v_cvt_f32_f16_e32 v58, v11
	v_cvt_f32_f16_sdwa v115, v15 dst_sel:DWORD dst_unused:UNUSED_PAD src0_sel:WORD_1
	v_cvt_f32_f16_e32 v114, v15
	v_cvt_f32_f16_sdwa v121, v19 dst_sel:DWORD dst_unused:UNUSED_PAD src0_sel:WORD_1
	v_cvt_f32_f16_e32 v120, v19
	v_pk_add_f32 v[118:119], v[72:73], v[58:59]
	ds_bpermute_b32 v56, v138, v108
	v_pk_add_f32 v[116:117], v[118:119], v[114:115]
	s_waitcnt lgkmcnt(0)
	v_pk_add_f32 v[114:115], v[116:117], v[120:121]
	ds_bpermute_b32 v58, v138, v115
	ds_bpermute_b32 v120, v138, v114
	v_cndmask_b32_e64 v56, v56, 0, s[4:5]
	v_pk_add_f32 v[56:57], v[108:109], v[56:57]
	ds_bpermute_b32 v122, v139, v56
	s_waitcnt lgkmcnt(2)
	v_cndmask_b32_e64 v59, v58, 0, s[4:5]
	s_waitcnt lgkmcnt(1)
	v_cndmask_b32_e64 v58, v120, 0, s[4:5]
	ds_bpermute_b32 v121, v139, v57
	v_pk_add_f32 v[58:59], v[114:115], v[58:59]
	ds_bpermute_b32 v123, v139, v59
	ds_bpermute_b32 v124, v139, v58
	s_waitcnt lgkmcnt(3)
	v_cndmask_b32_e64 v120, 0, v122, s[6:7]
	s_waitcnt lgkmcnt(2)
	v_cndmask_b32_e64 v121, 0, v121, s[6:7]
	v_pk_add_f32 v[56:57], v[56:57], v[120:121]
	s_waitcnt lgkmcnt(1)
	v_cndmask_b32_e64 v121, 0, v123, s[6:7]
	s_waitcnt lgkmcnt(0)
	v_cndmask_b32_e64 v120, 0, v124, s[6:7]
	v_pk_add_f32 v[58:59], v[58:59], v[120:121]
	s_barrier
	s_and_saveexec_b64 s[64:65], s[8:9]
	s_cbranch_execz .LBB0_405
	ds_write_b128 v155, v[52:55]
	ds_write_b128 v155, v[56:59] offset:16

; DI void hgrn_phase_c(const Params& p, LAS unsigned char* lds) {
;     ...
;         { const int nx = it + (int)gridDim.x;
;           if (nx < NITEMS) { const int n2 = nx % NCHUNK, bh2 = nx / NCHUNK, h2 = bh2 & 7, b2 = bh2 >> 3;
;               load_g4((const bf16_t*)(ws + OFF_GF) + ((size_t)b2 * LP + 128 * n2) * D + h2 * DH, w, dgrp, rsub, gnext); } }
.LBB0_415:
	s_add_i32 s92, s20, s54
	s_cmpk_gt_i32 s92, 0x107f
	s_cselect_b64 s[64:65], -1, 0
	s_and_b64 vcc, exec, s[64:65]
	s_cbranch_vccnz .LBB0_417
	s_mul_hi_i32 s3, s92, 0x3e0f83e1
	s_lshr_b32 s21, s3, 31
	s_ashr_i32 s3, s3, 3
	s_add_i32 s3, s3, s21
	s_mul_i32 s21, s3, 33
	s_sub_i32 s21, s92, s21
	s_ashr_i32 s58, s3, 3
	s_lshl_b32 s21, s21, 7
	s_mul_hi_i32 s59, s58, 0x1080
	s_mulk_i32 s58, 0x1080
	s_ashr_i32 s66, s21, 31
	s_add_u32 s58, s58, s21
	s_addc_u32 s59, s59, s66
	s_lshl_b64 s[58:59], s[58:59], 11
	s_add_u32 s21, s26, s58
	s_addc_u32 s59, s27, s59
	s_lshl_b32 s3, s3, 8
	s_and_b32 s3, s3, 0x700
	s_add_u32 s58, s21, s3
	s_addc_u32 s59, s59, 0
	v_lshl_add_u64 v[4:5], s[58:59], 0, v[82:83]
	v_lshl_add_u64 v[12:13], v[4:5], 0, v[84:85]
	v_add_co_u32_e32 v16, vcc, 0x1000, v12
	global_load_dwordx4 v[4:7], v[12:13], off nt
	global_load_dwordx4 v[8:11], v[12:13], off offset:2048 nt
	v_addc_co_u32_e32 v17, vcc, 0, v13, vcc
	global_load_dwordx4 v[12:15], v[16:17], off nt
	s_nop 0
	global_load_dwordx4 v[16:19], v[16:17], off offset:2048 nt

; #define LAS __attribute__((address_space(3)))
; DI unsigned pk2(float lo, float hi) { const f32x2_t v = {lo, hi}; const bf16x2_t b = __builtin_convertvector(v, bf16x2_t); return __builtin_bit_cast(unsigned, b); }
; DI float bf_at(const u32x4& v, int j) { return __uint_as_float((j & 1) ? (v[j >> 1] & 0xffff0000u) : (v[j >> 1] << 16)); }
; DI void hgrn_phase_c(const Params& p, LAS unsigned char* lds) {
;     ...
;         u32x4 qe[4];
; #pragma unroll
;         for (int rr = 0; rr < 4; ++rr) {
;             float qp[8], kp[8], qx[8];
; #pragma unroll
;             for (int j = 0; j < 8; ++j) { const float qv = bf_at(qw[rr], j), kv = bf_at(kw[rr], j);
;                 const float t = __builtin_amdgcn_exp2f(__builtin_amdgcn_fmed3f(bb[rr][j] - cc[j], -115.f, 115.f));
;                 qp[j] = qv * t; kp[j] = kv * __builtin_amdgcn_rcpf(t); qx[j] = qp[j] * ec[j]; }
;             u32x4 a; a.x = pk2(qp[0], qp[1]); a.y = pk2(qp[2], qp[3]); a.z = pk2(qp[4], qp[5]); a.w = pk2(qp[6], qp[7]);
;             u32x4 c; c.x = pk2(kp[0], kp[1]); c.y = pk2(kp[2], kp[3]); c.z = pk2(kp[4], kp[5]); c.w = pk2(kp[6], kp[7]);
;             *(LAS u32x4*)(lds + R1 + (row0 + rr) * RS + dgrp * 16) = a;
;             *(LAS u32x4*)(lds + R2 + (row0 + rr) * RS + dgrp * 16) = c;
;             qe[rr].x = pk2(qx[0], qx[1]); qe[rr].y = pk2(qx[2], qx[3]); qe[rr].z = pk2(qx[4], qx[5]); qe[rr].w = pk2(qx[6], qx[7]);
;         }
.LBB0_419:
	s_or_b64 exec, exec, s[66:67]
	s_waitcnt lgkmcnt(7)
	v_sub_f32_e32 v56, v56, v64
	s_waitcnt lgkmcnt(6)
	v_sub_f32_e32 v57, v57, v65
	v_med3_f32 v56, v56, s85, v165
	v_med3_f32 v57, v57, s85, v165
	v_exp_f32_e32 v56, v56
	v_exp_f32_e32 v57, v57
	v_add_f32_e32 v132, v62, v126
	v_add_f32_e32 v133, v63, v127
	s_waitcnt vmcnt(7)
	v_lshlrev_b32_e32 v62, 16, v48
	v_and_b32_e32 v63, 0xffff0000, v48
	v_add_f32_e32 v130, v68, v126
	v_add_f32_e32 v131, v69, v127
	v_add_f32_e32 v126, v60, v126
	v_add_f32_e32 v127, v61, v127
	v_rcp_f32_e32 v60, v56
	v_rcp_f32_e32 v61, v57
	v_pk_mul_f32 v[68:69], v[56:57], v[62:63]
	s_waitcnt vmcnt(6)
	v_lshlrev_b32_e32 v56, 16, v44
	v_and_b32_e32 v57, 0xffff0000, v44
	s_waitcnt lgkmcnt(5)
	v_sub_f32_e32 v44, v58, v66
	v_med3_f32 v44, v44, s85, v165
	v_exp_f32_e32 v58, v44
	s_waitcnt lgkmcnt(4)
	v_sub_f32_e32 v44, v59, v67
	v_med3_f32 v44, v44, s85, v165
	v_exp_f32_e32 v59, v44
	v_pk_mul_f32 v[56:57], v[60:61], v[56:57]
	v_rcp_f32_e32 v48, v58
	v_lshlrev_b32_e32 v60, 16, v49
	v_and_b32_e32 v61, 0xffff0000, v49
	v_rcp_f32_e32 v49, v59
	v_lshlrev_b32_e32 v44, 16, v45
	v_and_b32_e32 v45, 0xffff0000, v45
	v_pk_mul_f32 v[70:71], v[58:59], v[60:61]
	v_pk_mul_f32 v[58:59], v[48:49], v[44:45]
	s_waitcnt lgkmcnt(3)
	v_sub_f32_e32 v44, v52, v128
	s_waitcnt lgkmcnt(2)
	v_sub_f32_e32 v45, v53, v129
	v_med3_f32 v44, v44, s85, v165
	v_med3_f32 v45, v45, s85, v165
	v_exp_f32_e32 v44, v44
	v_exp_f32_e32 v45, v45
	v_lshlrev_b32_e32 v52, 16, v50
	v_and_b32_e32 v53, 0xffff0000, v50
	v_rcp_f32_e32 v48, v44
	v_rcp_f32_e32 v49, v45
	v_pk_mul_f32 v[72:73], v[44:45], v[52:53]
	v_lshlrev_b32_e32 v44, 16, v46
	v_and_b32_e32 v45, 0xffff0000, v46
	v_pk_mul_f32 v[52:53], v[48:49], v[44:45]
	s_waitcnt lgkmcnt(1)
	v_sub_f32_e32 v44, v54, v169
	s_waitcnt lgkmcnt(0)
	v_sub_f32_e32 v45, v55, v170
	v_med3_f32 v44, v44, s85, v165
	v_med3_f32 v45, v45, s85, v165
	v_exp_f32_e32 v44, v44
	v_exp_f32_e32 v45, v45
	v_lshlrev_b32_e32 v50, 16, v51
	v_and_b32_e32 v51, 0xffff0000, v51
	v_rcp_f32_e32 v48, v44
	v_rcp_f32_e32 v49, v45
	v_add_f32_e32 v78, v78, v124
	v_add_f32_e32 v79, v79, v125
	v_add_f32_e32 v134, v76, v124
	v_add_f32_e32 v135, v77, v125
	v_add_f32_e32 v124, v74, v124
	v_add_f32_e32 v125, v75, v125
	v_pk_mul_f32 v[74:75], v[44:45], v[50:51]
	v_lshlrev_b32_e32 v44, 16, v47
	v_and_b32_e32 v45, 0xffff0000, v47
	v_pk_mul_f32 v[54:55], v[48:49], v[44:45]
	v_cvt_pk_bf16_f32 v44, v68, v69
	v_cvt_pk_bf16_f32 v45, v70, v71
	v_cvt_pk_bf16_f32 v46, v72, v73
	v_cvt_pk_bf16_f32 v47, v74, v75
	v_cvt_pk_bf16_f32 v48, v56, v57
	v_cvt_pk_bf16_f32 v49, v58, v59
	v_cvt_pk_bf16_f32 v50, v52, v53
	v_cvt_pk_bf16_f32 v51, v54, v55
	ds_write_b128 v166, v[44:47]
	ds_write_b128 v166, v[48:51] offset:34816
	v_sub_f32_e32 v44, v130, v64
	v_sub_f32_e32 v45, v131, v65
	v_med3_f32 v44, v44, s85, v165
	v_med3_f32 v45, v45, s85, v165
	v_exp_f32_e32 v44, v44
	v_exp_f32_e32 v45, v45
	s_waitcnt vmcnt(5)
	v_lshlrev_b32_e32 v48, 16, v40
	v_and_b32_e32 v49, 0xffff0000, v40
	v_rcp_f32_e32 v46, v44
	v_rcp_f32_e32 v47, v45
	v_pk_mul_f32 v[76:77], v[44:45], v[48:49]
	s_waitcnt vmcnt(4)
	v_lshlrev_b32_e32 v44, 16, v36
	v_and_b32_e32 v45, 0xffff0000, v36
	v_sub_f32_e32 v36, v78, v66
	v_med3_f32 v36, v36, s85, v165
	v_pk_mul_f32 v[44:45], v[46:47], v[44:45]
	v_exp_f32_e32 v46, v36
	v_sub_f32_e32 v36, v79, v67
	v_med3_f32 v36, v36, s85, v165
	v_exp_f32_e32 v47, v36
	v_rcp_f32_e32 v40, v46
	v_lshlrev_b32_e32 v48, 16, v41
	v_and_b32_e32 v49, 0xffff0000, v41
	v_rcp_f32_e32 v41, v47
	v_add_f32_e32 v112, v112, v122
	v_add_f32_e32 v113, v113, v123
	v_lshlrev_b32_e32 v36, 16, v37
	v_and_b32_e32 v37, 0xffff0000, v37
	v_pk_mul_f32 v[78:79], v[46:47], v[48:49]
	v_pk_mul_f32 v[46:47], v[40:41], v[36:37]
	v_sub_f32_e32 v36, v112, v128
	v_sub_f32_e32 v37, v113, v129
	v_med3_f32 v36, v36, s85, v165
	v_med3_f32 v37, v37, s85, v165
	v_exp_f32_e32 v36, v36
	v_exp_f32_e32 v37, v37
	v_lshlrev_b32_e32 v48, 16, v42
	v_and_b32_e32 v49, 0xffff0000, v42
	v_rcp_f32_e32 v40, v36
	v_rcp_f32_e32 v41, v37
	v_add_f32_e32 v118, v118, v120
	v_add_f32_e32 v119, v119, v121
	v_add_f32_e32 v175, v108, v122
	v_add_f32_e32 v178, v109, v123
	v_pk_mul_f32 v[108:109], v[36:37], v[48:49]
	v_lshlrev_b32_e32 v36, 16, v38
	v_and_b32_e32 v37, 0xffff0000, v38
	v_pk_mul_f32 v[48:49], v[40:41], v[36:37]
	v_sub_f32_e32 v36, v118, v169
	v_sub_f32_e32 v37, v119, v170
	v_med3_f32 v36, v36, s85, v165
	v_med3_f32 v37, v37, s85, v165
	v_exp_f32_e32 v36, v36
	v_exp_f32_e32 v37, v37
	v_lshlrev_b32_e32 v42, 16, v43
	v_and_b32_e32 v43, 0xffff0000, v43
	v_rcp_f32_e32 v40, v36
	v_rcp_f32_e32 v41, v37
	v_add_f32_e32 v171, v110, v122
	v_add_f32_e32 v172, v111, v123
	v_pk_mul_f32 v[110:111], v[36:37], v[42:43]
	v_lshlrev_b32_e32 v36, 16, v39
	v_and_b32_e32 v37, 0xffff0000, v39
	v_pk_mul_f32 v[50:51], v[40:41], v[36:37]
	v_cvt_pk_bf16_f32 v36, v76, v77
	v_cvt_pk_bf16_f32 v37, v78, v79
	v_cvt_pk_bf16_f32 v38, v108, v109
	v_cvt_pk_bf16_f32 v39, v110, v111
	v_cvt_pk_bf16_f32 v40, v44, v45
	v_cvt_pk_bf16_f32 v41, v46, v47
	v_cvt_pk_bf16_f32 v42, v48, v49
	v_cvt_pk_bf16_f32 v43, v50, v51
	ds_write_b128 v166, v[36:39] offset:272
	ds_write_b128 v166, v[40:43] offset:35088
	v_sub_f32_e32 v36, v132, v64
	v_sub_f32_e32 v37, v133, v65
	v_med3_f32 v36, v36, s85, v165
	v_med3_f32 v37, v37, s85, v165
	v_exp_f32_e32 v36, v36
	v_exp_f32_e32 v37, v37
	s_waitcnt vmcnt(3)
; #define LAS __attribute__((address_space(3)))
; DI unsigned pk2(float lo, float hi) { const f32x2_t v = {lo, hi}; const bf16x2_t b = __builtin_convertvector(v, bf16x2_t); return __builtin_bit_cast(unsigned, b); }
; DI float bf_at(const u32x4& v, int j) { return __uint_as_float((j & 1) ? (v[j >> 1] & 0xffff0000u) : (v[j >> 1] << 16)); }
; DI void hgrn_phase_c(const Params& p, LAS unsigned char* lds) {
;     ...
;         u32x4 qe[4];
; #pragma unroll
;         for (int rr = 0; rr < 4; ++rr) {
;             float qp[8], kp[8], qx[8];
; #pragma unroll
;             for (int j = 0; j < 8; ++j) { const float qv = bf_at(qw[rr], j), kv = bf_at(kw[rr], j);
;                 const float t = __builtin_amdgcn_exp2f(__builtin_amdgcn_fmed3f(bb[rr][j] - cc[j], -115.f, 115.f));
;                 qp[j] = qv * t; kp[j] = kv * __builtin_amdgcn_rcpf(t); qx[j] = qp[j] * ec[j]; }
;             u32x4 a; a.x = pk2(qp[0], qp[1]); a.y = pk2(qp[2], qp[3]); a.z = pk2(qp[4], qp[5]); a.w = pk2(qp[6], qp[7]);
;             u32x4 c; c.x = pk2(kp[0], kp[1]); c.y = pk2(kp[2], kp[3]); c.z = pk2(kp[4], kp[5]); c.w = pk2(kp[6], kp[7]);
;             *(LAS u32x4*)(lds + R1 + (row0 + rr) * RS + dgrp * 16) = a;
;             *(LAS u32x4*)(lds + R2 + (row0 + rr) * RS + dgrp * 16) = c;
;             qe[rr].x = pk2(qx[0], qx[1]); qe[rr].y = pk2(qx[2], qx[3]); qe[rr].z = pk2(qx[4], qx[5]); qe[rr].w = pk2(qx[6], qx[7]);
;         }
;         __syncthreads();
;         bf16x8 sf[4]; u32x4 vw[4];
; #pragma unroll
;         for (int ks = 0; ks < 4; ++ks) sf[ks] = *(const bf16x8*)(St + (16 * w + l15) * 128 + 32 * ks + 8 * g4);
; #pragma unroll
;         for (int rr = 0; rr < 4; ++rr) vw[rr] = *(const u32x4*)(Vg + (size_t)(row0 + rr) * D + 8 * dgrp);
	v_lshlrev_b32_e32 v40, 16, v32
	v_and_b32_e32 v41, 0xffff0000, v32
	v_rcp_f32_e32 v38, v36
	v_rcp_f32_e32 v39, v37
	v_pk_mul_f32 v[112:113], v[36:37], v[40:41]
	s_waitcnt vmcnt(2)
	v_lshlrev_b32_e32 v36, 16, v28
	v_and_b32_e32 v37, 0xffff0000, v28
	v_sub_f32_e32 v28, v134, v66
	v_med3_f32 v28, v28, s85, v165
	v_pk_mul_f32 v[36:37], v[38:39], v[36:37]
	v_exp_f32_e32 v38, v28
	v_sub_f32_e32 v28, v135, v67
	v_med3_f32 v28, v28, s85, v165
	v_exp_f32_e32 v39, v28
	v_rcp_f32_e32 v32, v38
	v_lshlrev_b32_e32 v40, 16, v33
	v_and_b32_e32 v41, 0xffff0000, v33
	v_rcp_f32_e32 v33, v39
	v_lshlrev_b32_e32 v28, 16, v29
	v_and_b32_e32 v29, 0xffff0000, v29
	v_add_f32_e32 v179, v114, v120
	v_add_f32_e32 v180, v115, v121
	v_pk_mul_f32 v[114:115], v[38:39], v[40:41]
	v_pk_mul_f32 v[38:39], v[32:33], v[28:29]
	v_sub_f32_e32 v28, v171, v128
	v_sub_f32_e32 v29, v172, v129
	v_med3_f32 v28, v28, s85, v165
	v_med3_f32 v29, v29, s85, v165
	v_exp_f32_e32 v28, v28
	v_exp_f32_e32 v29, v29
	v_lshlrev_b32_e32 v40, 16, v34
	v_and_b32_e32 v41, 0xffff0000, v34
	v_rcp_f32_e32 v32, v28
	v_rcp_f32_e32 v33, v29
	v_add_f32_e32 v173, v116, v120
	v_add_f32_e32 v174, v117, v121
	v_pk_mul_f32 v[116:117], v[28:29], v[40:41]
	v_lshlrev_b32_e32 v28, 16, v30
	v_and_b32_e32 v29, 0xffff0000, v30
	v_pk_mul_f32 v[40:41], v[32:33], v[28:29]
	v_sub_f32_e32 v28, v173, v169
	v_sub_f32_e32 v29, v174, v170
	v_med3_f32 v28, v28, s85, v165
	v_med3_f32 v29, v29, s85, v165
	v_exp_f32_e32 v28, v28
	v_exp_f32_e32 v29, v29
	v_lshlrev_b32_e32 v34, 16, v35
	v_and_b32_e32 v35, 0xffff0000, v35
	v_rcp_f32_e32 v32, v28
	v_rcp_f32_e32 v33, v29
	v_pk_mul_f32 v[118:119], v[28:29], v[34:35]
	v_lshlrev_b32_e32 v28, 16, v31
	v_and_b32_e32 v29, 0xffff0000, v31
	v_pk_mul_f32 v[42:43], v[32:33], v[28:29]
	v_cvt_pk_bf16_f32 v28, v112, v113
	v_cvt_pk_bf16_f32 v29, v114, v115
	v_cvt_pk_bf16_f32 v30, v116, v117
	v_cvt_pk_bf16_f32 v31, v118, v119
	v_cvt_pk_bf16_f32 v32, v36, v37
	v_cvt_pk_bf16_f32 v33, v38, v39
	v_cvt_pk_bf16_f32 v34, v40, v41
	v_cvt_pk_bf16_f32 v35, v42, v43
	ds_write_b128 v166, v[28:31] offset:544
	ds_write_b128 v166, v[32:35] offset:35360
	v_sub_f32_e32 v28, v126, v64
	v_sub_f32_e32 v29, v127, v65
	v_med3_f32 v28, v28, s85, v165
	v_med3_f32 v29, v29, s85, v165
	v_exp_f32_e32 v28, v28
	v_exp_f32_e32 v29, v29
	s_waitcnt vmcnt(1)
	v_lshlrev_b32_e32 v32, 16, v24
	v_and_b32_e32 v33, 0xffff0000, v24
	v_rcp_f32_e32 v30, v28
	v_rcp_f32_e32 v31, v29
	v_pk_mul_f32 v[120:121], v[28:29], v[32:33]
	s_waitcnt vmcnt(0)
	v_lshlrev_b32_e32 v28, 16, v20
	v_and_b32_e32 v29, 0xffff0000, v20
	v_sub_f32_e32 v20, v124, v66
	v_med3_f32 v20, v20, s85, v165
	v_pk_mul_f32 v[28:29], v[30:31], v[28:29]
	v_exp_f32_e32 v30, v20
	v_sub_f32_e32 v20, v125, v67
	v_med3_f32 v20, v20, s85, v165
	v_exp_f32_e32 v31, v20
	v_rcp_f32_e32 v24, v30
	v_lshlrev_b32_e32 v32, 16, v25
	v_and_b32_e32 v33, 0xffff0000, v25
	v_rcp_f32_e32 v25, v31
	v_lshlrev_b32_e32 v20, 16, v21
	v_and_b32_e32 v21, 0xffff0000, v21
	v_pk_mul_f32 v[122:123], v[30:31], v[32:33]
	v_pk_mul_f32 v[30:31], v[24:25], v[20:21]
	v_sub_f32_e32 v20, v175, v128
	v_sub_f32_e32 v21, v178, v129
	v_med3_f32 v20, v20, s85, v165
	v_med3_f32 v21, v21, s85, v165
	v_exp_f32_e32 v20, v20
	v_exp_f32_e32 v21, v21
	v_lshlrev_b32_e32 v32, 16, v26
	v_and_b32_e32 v33, 0xffff0000, v26
	v_rcp_f32_e32 v24, v20
	v_rcp_f32_e32 v25, v21
	v_pk_mul_f32 v[124:125], v[20:21], v[32:33]
	v_lshlrev_b32_e32 v20, 16, v22
	v_and_b32_e32 v21, 0xffff0000, v22
	v_pk_mul_f32 v[32:33], v[24:25], v[20:21]
	v_sub_f32_e32 v20, v179, v169
	v_sub_f32_e32 v21, v180, v170
	v_med3_f32 v20, v20, s85, v165
	v_med3_f32 v21, v21, s85, v165
	v_exp_f32_e32 v20, v20
	v_exp_f32_e32 v21, v21
	v_lshlrev_b32_e32 v26, 16, v27
	v_and_b32_e32 v27, 0xffff0000, v27
	v_rcp_f32_e32 v24, v20
	v_rcp_f32_e32 v25, v21
	s_ashr_i32 s21, s20, 31
	v_pk_mul_f32 v[126:127], v[20:21], v[26:27]
	v_lshlrev_b32_e32 v20, 16, v23
	v_and_b32_e32 v21, 0xffff0000, v23
	s_lshl_b64 s[20:21], s[20:21], 15
	v_pk_mul_f32 v[34:35], v[24:25], v[20:21]
	v_cvt_pk_bf16_f32 v20, v120, v121
	v_cvt_pk_bf16_f32 v21, v122, v123
	v_cvt_pk_bf16_f32 v22, v124, v125
	v_cvt_pk_bf16_f32 v23, v126, v127
	v_cvt_pk_bf16_f32 v24, v28, v29
	v_cvt_pk_bf16_f32 v25, v30, v31
	v_cvt_pk_bf16_f32 v26, v32, v33
	v_cvt_pk_bf16_f32 v27, v34, v35
	ds_write_b128 v166, v[20:23] offset:816
	ds_write_b128 v166, v[24:27] offset:35632
	v_lshl_add_u64 v[20:21], v[90:91], 0, s[20:21]
	s_waitcnt lgkmcnt(0)
	s_barrier
	global_load_dwordx4 v[60:63], v[20:21], off
	global_load_dwordx4 v[28:31], v[20:21], off offset:64
	global_load_dwordx4 v[24:27], v[20:21], off offset:128
	s_nop 0
	global_load_dwordx4 v[20:23], v[20:21], off offset:192
	v_lshl_add_u64 v[40:41], s[0:1], 1, v[92:93]
	v_lshl_add_u64 v[32:33], v[40:41], 0, v[82:83]
	v_lshl_add_u64 v[36:37], v[40:41], 0, v[94:95]
	v_lshl_add_u64 v[42:43], v[40:41], 0, v[96:97]
	v_lshl_add_u64 v[44:45], v[40:41], 0, v[98:99]
	global_load_dwordx4 v[32:35], v[32:33], off nt
	s_nop 0
	global_load_dwordx4 v[36:39], v[36:37], off nt
	s_nop 0
	global_load_dwordx4 v[40:43], v[42:43], off nt
	s_nop 0
	global_load_dwordx4 v[44:47], v[44:45], off nt
	v_exp_f32_e32 v130, v64
	v_exp_f32_e32 v131, v65
	v_exp_f32_e32 v132, v66
	v_exp_f32_e32 v133, v67
	v_exp_f32_e32 v134, v128
	v_exp_f32_e32 v135, v129
	v_exp_f32_e32 v128, v169
	v_exp_f32_e32 v129, v170
	s_mov_b32 s0, 0
